# N1/N2 RMSNorm row loops: gain vector loaded once before the loop instead of four load+vmcnt(0) round trips (which also waited for store acks) per row pair
# speedup vs baseline: 1.0043x; 1.0019x over previous
; __device__ __forceinline__ void rms_row2(const float* xa, const float* xb, const float* g, bf16_t* oa, bf16_t* ob, int lane) {
;     const f32x4* pa = (const f32x4*)xa + lane; const f32x4* pb = (const f32x4*)xb + lane; f32x4 va[4], vb[4]; float sa = 0.f, sb = 0.f;
; #pragma unroll
;     for (int j = 0; j < 4; ++j) { va[j] = pa[64 * j]; vb[j] = pb[64 * j]; }
; #pragma unroll
;     for (int j = 0; j < 4; ++j) { sa += (va[j].x * va[j].x + va[j].y * va[j].y) + (va[j].z * va[j].z + va[j].w * va[j].w); sb += (vb[j].x * vb[j].x + vb[j].y * vb[j].y) + (vb[j].z * vb[j].z + vb[j].w * vb[j].w); }
; __global__ void __launch_bounds__(512, 2) fwd_kernel(Args a) {
;     ...
;         for (int m = gwo; m < MT; m += 2 * NGW) {
;             const int m2 = (m + NGW < MT) ? m + NGW : m;
;             const float* xa = (l == 0) ? (m < MP ? a.in[I_XP] + (size_t)m * 1024 : a.in[I_XS] + (size_t)(m - MP) * 1024) : Y + (size_t)m * 1024;
;             const float* xb = (l == 0) ? (m2 < MP ? a.in[I_XP] + (size_t)m2 * 1024 : a.in[I_XS] + (size_t)(m2 - MP) * 1024) : Y + (size_t)m2 * 1024;
;             rms_row2(xa, xb, a.in[I_N1G] + l * 1024, XN + (size_t)m * 1024, XN + (size_t)m2 * 1024, ln);
.LBB0_50:
	v_writelane_b32 v255, s4, 1
	s_xor_b64 s[0:1], s[4:5], -1
	v_mov_b32_e32 v18, v197
	v_writelane_b32 v255, s5, 2
	v_writelane_b32 v255, s0, 3
	s_nop 1
	v_writelane_b32 v255, s1, 4
	v_readlane_b32 s0, v252, 54
	s_cmp_gt_i32 s0, 0x80ff
	v_ashrrev_i32_e32 v19, 31, v18
	s_cbranch_scc1 .LBB0_67
	s_lshl_b32 s90, s24, 10
	v_readlane_b32 s36, v252, 6
	s_lshl_b64 s[4:5], s[90:91], 2
	v_readlane_b32 s48, v252, 18
	v_readlane_b32 s49, v252, 19
	s_add_u32 s4, s48, s4
	s_addc_u32 s5, s49, s5
	s_ashr_i32 s1, s0, 31
	v_lshl_add_u64 v[22:23], v[18:19], 4, s[4:5]
	global_load_dwordx4 v[66:69], v[22:23], off
	global_load_dwordx4 v[70:73], v[22:23], off offset:1024
	global_load_dwordx4 v[74:77], v[22:23], off offset:2048
	global_load_dwordx4 v[78:81], v[22:23], off offset:3072
	s_lshl_b64 s[4:5], s[0:1], 11
	v_readlane_b32 s6, v254, 38
	s_add_u32 s4, s6, s4
	v_readlane_b32 s6, v254, 39
	v_lshlrev_b64 v[2:3], 3, v[18:19]
	s_addc_u32 s5, s6, s5
	v_lshl_add_u64 v[20:21], s[20:21], 0, v[2:3]
	v_lshl_add_u64 v[24:25], s[4:5], 0, v[2:3]
	s_mov_b64 s[4:5], 0
	v_lshlrev_b64 v[26:27], 4, v[18:19]
	s_mov_b32 s6, s0
	v_readlane_b32 s37, v252, 7
	v_readlane_b32 s38, v252, 8
	v_readlane_b32 s39, v252, 9
	v_readlane_b32 s40, v252, 10
	v_readlane_b32 s41, v252, 11
	v_readlane_b32 s42, v252, 12
	v_readlane_b32 s43, v252, 13
	v_readlane_b32 s44, v252, 14
	v_readlane_b32 s45, v252, 15
	v_readlane_b32 s46, v252, 16
	v_readlane_b32 s47, v252, 17
	v_readlane_b32 s50, v252, 20
	v_readlane_b32 s51, v252, 21
	s_branch .LBB0_53
.LBB0_52:
	v_lshl_add_u64 v[2:3], s[14:15], 0, v[26:27]
	global_load_dwordx4 v[30:33], v[2:3], off
	global_load_dwordx4 v[34:37], v[2:3], off offset:1024
	global_load_dwordx4 v[10:13], v[2:3], off offset:2048
	s_nop 0
	global_load_dwordx4 v[2:5], v[2:3], off offset:3072
	s_lshl_b64 s[12:13], s[12:13], 12
	s_add_u32 s10, s10, s12
	s_addc_u32 s11, s11, s13
	v_lshl_add_u64 v[6:7], s[10:11], 0, v[26:27]
	global_load_dwordx4 v[38:41], v[6:7], off
	global_load_dwordx4 v[42:45], v[6:7], off offset:1024
	global_load_dwordx4 v[14:17], v[6:7], off offset:2048
	s_nop 0
	global_load_dwordx4 v[6:9], v[6:7], off offset:3072
	s_lshl_b64 s[8:9], s[8:9], 11
	s_add_i32 s6, s6, s70
	s_add_u32 s4, s4, s70
	s_addc_u32 s5, s5, s71
	s_cmp_gt_i32 s6, 0x80ff
	s_waitcnt vmcnt(7)
	v_mul_f32_e32 v0, v31, v31
	v_mul_f32_e32 v28, v33, v33
	s_waitcnt vmcnt(6)
	v_mul_f32_e32 v29, v35, v35
	v_mul_f32_e32 v46, v37, v37
	s_waitcnt vmcnt(5)
	v_mul_f32_e32 v47, v11, v11
	v_mul_f32_e32 v48, v13, v13
	s_waitcnt vmcnt(4)
	v_mul_f32_e32 v49, v3, v3
	v_mul_f32_e32 v50, v5, v5
	v_fmac_f32_e32 v0, v30, v30
	v_fmac_f32_e32 v28, v32, v32
	v_fmac_f32_e32 v29, v34, v34
	v_fmac_f32_e32 v46, v36, v36
	v_fmac_f32_e32 v47, v10, v10
	v_fmac_f32_e32 v48, v12, v12
	v_fmac_f32_e32 v49, v2, v2
	v_fmac_f32_e32 v50, v4, v4
	v_add_f32_e32 v0, v0, v28
	v_add_f32_e32 v28, v29, v46
	v_add_f32_e32 v29, v47, v48
	v_add_f32_e32 v46, v49, v50
	s_waitcnt vmcnt(3)
	v_mul_f32_e32 v47, v39, v39
	v_mul_f32_e32 v48, v41, v41
	s_waitcnt vmcnt(2)
	v_mul_f32_e32 v49, v43, v43
	v_mul_f32_e32 v50, v45, v45
	v_add_f32_e32 v0, v0, v28
	s_waitcnt vmcnt(1)
	v_mul_f32_e32 v28, v15, v15
	v_mul_f32_e32 v51, v17, v17
	v_fmac_f32_e32 v47, v38, v38
	v_fmac_f32_e32 v48, v40, v40
	v_fmac_f32_e32 v49, v42, v42
	v_fmac_f32_e32 v50, v44, v44
	s_waitcnt vmcnt(0)
; __device__ __forceinline__ float wave_sum(float v) { v = dpp_add(v, 0); v = dpp_add(v, 1); v = dpp_add(v, 2); v = dpp_add(v, 3); v = x16_sum(v); return x32_sum(v); }
; __device__ __forceinline__ unsigned f2bf(float f) { unsigned u = __builtin_bit_cast(unsigned, f); return (u + 0x7fffu + ((u >> 16) & 1u)) >> 16; }
; __device__ __forceinline__ unsigned pk2(float lo, float hi) { return f2bf(lo) | (f2bf(hi) << 16); }
; __device__ __forceinline__ void rms_row2(const float* xa, const float* xb, const float* g, bf16_t* oa, bf16_t* ob, int lane) {
;     ...
;     const float ra = __builtin_amdgcn_rsqf(wave_sum(sa) * (1.f / 1024.f) + EPS), rb = __builtin_amdgcn_rsqf(wave_sum(sb) * (1.f / 1024.f) + EPS);
;     u32x2* qa = (u32x2*)oa + lane; u32x2* qb = (u32x2*)ob + lane;
; #pragma unroll
;     for (int j = 0; j < 4; ++j) { const f32x4 gg = ((const f32x4*)g)[64 * j + lane]; const f32x4 ta = va[j] * ra * gg, tb = vb[j] * rb * gg;
;         u32x2 p; p.x = pk2(ta.x, ta.y); p.y = pk2(ta.z, ta.w); qa[64 * j] = p; u32x2 q; q.x = pk2(tb.x, tb.y); q.y = pk2(tb.z, tb.w); qb[64 * j] = q; }
; }
	v_mul_f32_e32 v52, v7, v7
	v_mul_f32_e32 v53, v9, v9
	v_fmac_f32_e32 v28, v14, v14
	v_fmac_f32_e32 v51, v16, v16
	v_add_f32_e32 v0, v0, v29
	v_add_f32_e32 v29, v47, v48
	v_add_f32_e32 v47, v49, v50
	v_fmac_f32_e32 v52, v6, v6
	v_fmac_f32_e32 v53, v8, v8
	v_add_f32_e32 v28, v28, v51
	v_add_f32_e32 v29, v29, v47
	v_add_f32_e32 v48, v52, v53
	v_add_f32_e32 v28, v29, v28
	v_add_f32_e32 v28, v28, v48
	v_add_f32_e32 v0, v0, v46
	s_nop 0
	v_add_f32_dpp v28, v28, v28 quad_perm:[1,0,3,2] row_mask:0xf bank_mask:0xf bound_ctrl:1
	v_add_f32_dpp v0, v0, v0 quad_perm:[1,0,3,2] row_mask:0xf bank_mask:0xf bound_ctrl:1
	s_nop 0
	v_add_f32_dpp v28, v28, v28 quad_perm:[2,3,0,1] row_mask:0xf bank_mask:0xf bound_ctrl:1
	v_add_f32_dpp v0, v0, v0 quad_perm:[2,3,0,1] row_mask:0xf bank_mask:0xf bound_ctrl:1
	s_nop 0
	v_add_f32_dpp v28, v28, v28 row_half_mirror row_mask:0xf bank_mask:0xf bound_ctrl:1
	v_add_f32_dpp v0, v0, v0 row_half_mirror row_mask:0xf bank_mask:0xf bound_ctrl:1
	s_nop 0
	v_add_f32_dpp v28, v28, v28 row_mirror row_mask:0xf bank_mask:0xf bound_ctrl:1
	v_mov_b32_e32 v46, v28
	s_nop 1
	v_permlane16_swap_b32 v28, v46
	s_nop 1
	v_add_f32_dpp v0, v0, v0 row_mirror row_mask:0xf bank_mask:0xf bound_ctrl:1
	v_add_f32_e32 v28, v28, v46
	v_mov_b32_e32 v29, v0
	v_mov_b32_e32 v50, v28
	s_nop 1
	v_permlane32_swap_b32 v28, v50
	s_nop 1
	s_nop 1
	v_permlane16_swap_b32 v0, v29
	s_nop 1
	s_nop 0
	v_add_f32_e32 v29, v0, v29
	v_mov_b32_e32 v51, v29
	s_nop 1
	v_permlane32_swap_b32 v29, v51
	s_nop 1
	v_add_f32_e32 v0, v28, v50
	v_fmamk_f32 v0, v0, 0x3a800000, v198
	v_add_f32_e32 v28, v29, v51
	v_rsq_f32_e32 v0, v0
	v_fmamk_f32 v28, v28, 0x3a800000, v198
	v_rsq_f32_e32 v50, v28
	v_lshl_add_u64 v[28:29], v[20:21], 0, s[8:9]
	v_pk_mul_f32 v[38:39], v[38:39], v[0:1] op_sel_hi:[1,0]
	v_pk_mul_f32 v[40:41], v[40:41], v[0:1] op_sel_hi:[1,0]
	v_pk_mul_f32 v[30:31], v[30:31], v[50:51] op_sel_hi:[1,0]
	v_pk_mul_f32 v[32:33], v[32:33], v[50:51] op_sel_hi:[1,0]
	v_pk_mul_f32 v[14:15], v[14:15], v[0:1] op_sel_hi:[1,0]
	v_pk_mul_f32 v[16:17], v[16:17], v[0:1] op_sel_hi:[1,0]
	v_pk_mul_f32 v[6:7], v[6:7], v[0:1] op_sel_hi:[1,0]
	v_pk_mul_f32 v[8:9], v[8:9], v[0:1] op_sel_hi:[1,0]
	v_readlane_b32 s8, v254, 40
	v_readlane_b32 s9, v254, 41
	v_pk_mul_f32 v[40:41], v[68:69], v[40:41]
	v_pk_mul_f32 v[38:39], v[66:67], v[38:39]
	v_pk_mul_f32 v[32:33], v[68:69], v[32:33]
	v_pk_mul_f32 v[30:31], v[66:67], v[30:31]
	v_bfe_u32 v46, v38, 16, 1
	v_bfe_u32 v48, v40, 16, 1
	v_bfe_u32 v47, v39, 16, 1
	v_bfe_u32 v49, v41, 16, 1
	v_bfe_u32 v51, v30, 16, 1
	v_bfe_u32 v52, v31, 16, 1
	v_bfe_u32 v53, v32, 16, 1
	v_add3_u32 v38, v38, v46, s31
	v_add3_u32 v40, v40, v48, s31
	v_bfe_u32 v54, v33, 16, 1
	v_add3_u32 v39, v39, v47, s31
	v_add3_u32 v41, v41, v49, s31
	v_add3_u32 v30, v30, v51, s31
	v_add3_u32 v46, v31, v52, s31
	v_add3_u32 v31, v32, v53, s31
	v_lshrrev_b32_e32 v32, 16, v38
	v_lshrrev_b32_e32 v38, 16, v40
	v_add3_u32 v33, v33, v54, s31
	v_lshrrev_b32_e32 v40, 16, v30
	v_lshrrev_b32_e32 v47, 16, v31
	v_and_or_b32 v30, v39, s77, v32
	v_and_or_b32 v31, v41, s77, v38
	v_and_or_b32 v32, v46, s77, v40
	v_and_or_b32 v33, v33, s77, v47
	global_store_dwordx2 v[24:25], v[30:31], off offset:-1536
	global_store_dwordx2 v[28:29], v[32:33], off
	v_pk_mul_f32 v[38:39], v[42:43], v[0:1] op_sel_hi:[1,0]
	v_pk_mul_f32 v[40:41], v[44:45], v[0:1] op_sel_hi:[1,0]
	v_pk_mul_f32 v[34:35], v[34:35], v[50:51] op_sel_hi:[1,0]
	v_pk_mul_f32 v[36:37], v[36:37], v[50:51] op_sel_hi:[1,0]
	v_pk_mul_f32 v[10:11], v[10:11], v[50:51] op_sel_hi:[1,0]
	v_pk_mul_f32 v[12:13], v[12:13], v[50:51] op_sel_hi:[1,0]
	v_pk_mul_f32 v[2:3], v[2:3], v[50:51] op_sel_hi:[1,0]
	v_pk_mul_f32 v[4:5], v[4:5], v[50:51] op_sel_hi:[1,0]
	v_pk_mul_f32 v[40:41], v[40:41], v[72:73]
	v_pk_mul_f32 v[38:39], v[38:39], v[70:71]
	v_pk_mul_f32 v[32:33], v[72:73], v[36:37]
	v_pk_mul_f32 v[30:31], v[70:71], v[34:35]
	v_bfe_u32 v34, v38, 16, 1
	v_bfe_u32 v36, v40, 16, 1
	v_bfe_u32 v35, v39, 16, 1
	v_bfe_u32 v37, v41, 16, 1
	v_bfe_u32 v42, v30, 16, 1
	v_bfe_u32 v43, v31, 16, 1
	v_bfe_u32 v44, v32, 16, 1
	v_add3_u32 v34, v38, v34, s31
	v_add3_u32 v36, v40, v36, s31
	v_bfe_u32 v45, v33, 16, 1
	v_add3_u32 v35, v39, v35, s31
	v_add3_u32 v37, v41, v37, s31
	v_add3_u32 v30, v30, v42, s31
	v_add3_u32 v38, v31, v43, s31
	v_add3_u32 v31, v32, v44, s31
	v_lshrrev_b32_e32 v32, 16, v34
	v_lshrrev_b32_e32 v34, 16, v36
	v_add3_u32 v33, v33, v45, s31
	v_lshrrev_b32_e32 v36, 16, v30
	v_lshrrev_b32_e32 v39, 16, v31
	v_and_or_b32 v30, v35, s77, v32
	v_and_or_b32 v31, v37, s77, v34
	v_and_or_b32 v32, v38, s77, v36
	v_and_or_b32 v33, v33, s77, v39
	global_store_dwordx2 v[24:25], v[30:31], off offset:-1024
	global_store_dwordx2 v[28:29], v[32:33], off offset:512
	v_pk_mul_f32 v[16:17], v[16:17], v[76:77]
	v_pk_mul_f32 v[14:15], v[14:15], v[74:75]
	v_pk_mul_f32 v[12:13], v[76:77], v[12:13]
	v_pk_mul_f32 v[10:11], v[74:75], v[10:11]
	v_bfe_u32 v30, v14, 16, 1
	v_bfe_u32 v32, v16, 16, 1
	v_bfe_u32 v31, v15, 16, 1
	v_bfe_u32 v33, v17, 16, 1
	v_bfe_u32 v34, v10, 16, 1
	v_bfe_u32 v35, v11, 16, 1
	v_bfe_u32 v36, v12, 16, 1
	v_add3_u32 v14, v14, v30, s31
	v_add3_u32 v16, v16, v32, s31
	v_bfe_u32 v37, v13, 16, 1
	v_add3_u32 v15, v15, v31, s31
	v_add3_u32 v17, v17, v33, s31
	v_add3_u32 v10, v10, v34, s31
	v_add3_u32 v30, v11, v35, s31
	v_add3_u32 v11, v12, v36, s31
	v_lshrrev_b32_e32 v12, 16, v14
	v_lshrrev_b32_e32 v14, 16, v16
	v_add3_u32 v13, v13, v37, s31
	v_lshrrev_b32_e32 v16, 16, v10
	v_lshrrev_b32_e32 v31, 16, v11
	v_and_or_b32 v10, v15, s77, v12
	v_and_or_b32 v11, v17, s77, v14
	v_and_or_b32 v12, v30, s77, v16
	v_and_or_b32 v13, v13, s77, v31
	global_store_dwordx2 v[24:25], v[10:11], off offset:-512
	global_store_dwordx2 v[28:29], v[12:13], off offset:1024
	v_pk_mul_f32 v[8:9], v[8:9], v[80:81]
	v_pk_mul_f32 v[6:7], v[6:7], v[78:79]
	v_pk_mul_f32 v[4:5], v[4:5], v[80:81]
	v_pk_mul_f32 v[2:3], v[2:3], v[78:79]
	v_bfe_u32 v0, v6, 16, 1
	v_bfe_u32 v10, v7, 16, 1
	v_bfe_u32 v11, v8, 16, 1
	v_bfe_u32 v12, v9, 16, 1
	v_bfe_u32 v13, v2, 16, 1
	v_bfe_u32 v14, v3, 16, 1
	v_bfe_u32 v15, v4, 16, 1
	v_add3_u32 v0, v6, v0, s31
	v_add3_u32 v6, v7, v10, s31
	v_add3_u32 v7, v8, v11, s31
	v_bfe_u32 v16, v5, 16, 1
	v_add3_u32 v8, v9, v12, s31
	v_add3_u32 v2, v2, v13, s31
	v_add3_u32 v9, v3, v14, s31
	v_add3_u32 v3, v4, v15, s31
	v_lshrrev_b32_e32 v0, 16, v0
	v_lshrrev_b32_e32 v4, 16, v7
	v_add3_u32 v5, v5, v16, s31
	v_lshrrev_b32_e32 v7, 16, v2
	v_lshrrev_b32_e32 v10, 16, v3
	v_and_or_b32 v2, v6, s77, v0
	v_and_or_b32 v3, v8, s77, v4
	v_and_or_b32 v4, v9, s77, v7
	v_and_or_b32 v5, v5, s77, v10
	global_store_dwordx2 v[24:25], v[2:3], off
	global_store_dwordx2 v[28:29], v[4:5], off offset:1536
	v_lshl_add_u64 v[24:25], v[24:25], 0, s[8:9]
	s_cbranch_scc1 .LBB0_67

; __device__ __forceinline__ void rms_row2(const float* xa, const float* xb, const float* g, bf16_t* oa, bf16_t* ob, int lane) {
;     const f32x4* pa = (const f32x4*)xa + lane; const f32x4* pb = (const f32x4*)xb + lane; f32x4 va[4], vb[4]; float sa = 0.f, sb = 0.f;
; #pragma unroll
;     for (int j = 0; j < 4; ++j) { va[j] = pa[64 * j]; vb[j] = pb[64 * j]; }
; #pragma unroll
;     for (int j = 0; j < 4; ++j) { sa += (va[j].x * va[j].x + va[j].y * va[j].y) + (va[j].z * va[j].z + va[j].w * va[j].w); sb += (vb[j].x * vb[j].x + vb[j].y * vb[j].y) + (vb[j].z * vb[j].z + vb[j].w * vb[j].w); }
; __global__ void __launch_bounds__(512, 2) fwd_kernel(Args a) {
;     ...
;           for (int m = gwo2; m < MT; m += 2 * NGW) { const int m2 = (m + NGW < MT) ? m + NGW : m;
;               rms_row2(X1 + (size_t)m * 1024, X1 + (size_t)m2 * 1024, a.in[I_N2G] + l * 1024, XN + (size_t)m * 1024, XN + (size_t)m2 * 1024, ln2); }
.LBB0_580:
	s_or_b64 exec, exec, s[0:1]
	v_mov_b32_e32 v34, v197
	v_readlane_b32 s0, v252, 54
	s_barrier
	s_cmp_gt_i32 s0, 0x80ff
	v_ashrrev_i32_e32 v35, 31, v34
	s_cbranch_scc1 .LBB0_583
	v_readlane_b32 s6, v255, 8
	v_readlane_b32 s36, v252, 38
	v_readlane_b32 s7, v255, 9
	s_lshl_b32 s90, s6, 10
	v_readlane_b32 s48, v252, 50
	v_readlane_b32 s49, v252, 51
	s_lshl_b64 s[6:7], s[90:91], 2
	s_mov_b64 s[24:25], s[48:49]
	s_add_u32 s6, s24, s6
	s_addc_u32 s7, s25, s7
	v_lshlrev_b64 v[2:3], 4, v[34:35]
	s_ashr_i32 s1, s0, 31
	v_lshlrev_b64 v[4:5], 3, v[34:35]
	v_lshl_add_u64 v[40:41], s[6:7], 0, v[2:3]
	global_load_dwordx4 v[66:69], v[40:41], off
	global_load_dwordx4 v[70:73], v[40:41], off offset:1024
	global_load_dwordx4 v[74:77], v[40:41], off offset:2048
	global_load_dwordx4 v[78:81], v[40:41], off offset:3072
	s_lshl_b64 s[6:7], s[0:1], 11
	v_readlane_b32 s38, v252, 40
	v_readlane_b32 s10, v254, 63
	v_lshl_add_u64 v[42:43], s[6:7], 0, v[4:5]
	s_lshl_b64 s[6:7], s[0:1], 12
	v_readlane_b32 s11, v255, 0
	s_movk_i32 s38, 0xffe0
	v_lshl_add_u64 v[36:37], s[34:35], 0, v[2:3]
	v_lshl_add_u64 v[38:39], s[20:21], 0, v[4:5]
	v_lshl_add_u64 v[44:45], s[6:7], 0, v[2:3]
	s_mov_b32 s1, s0
	v_readlane_b32 s37, v252, 39
	v_readlane_b32 s39, v252, 41
	v_readlane_b32 s40, v252, 42
	v_readlane_b32 s41, v252, 43
	v_readlane_b32 s42, v252, 44
	v_readlane_b32 s43, v252, 45
	v_readlane_b32 s44, v252, 46
	v_readlane_b32 s45, v252, 47
	v_readlane_b32 s46, v252, 48
	v_readlane_b32 s47, v252, 49
	v_readlane_b32 s50, v252, 52
	v_readlane_b32 s51, v252, 53
.LBB0_582:
	s_add_i32 s6, s82, s1
	s_cmp_lt_i32 s6, 0x8100
	s_cselect_b32 s6, s6, s1
	s_ashr_i32 s7, s6, 31
	v_lshl_add_u64 v[2:3], s[18:19], 0, v[44:45]
	s_lshl_b64 s[8:9], s[6:7], 12
	v_add_co_u32_e32 v2, vcc, 0x8500000, v2
	v_lshl_add_u64 v[4:5], v[36:37], 0, s[8:9]
	s_nop 0
	v_addc_co_u32_e32 v3, vcc, 0, v3, vcc
	global_load_dwordx4 v[30:33], v[2:3], off
	global_load_dwordx4 v[26:29], v[4:5], off
	global_load_dwordx4 v[22:25], v[2:3], off offset:1024
	global_load_dwordx4 v[18:21], v[4:5], off offset:1024
	global_load_dwordx4 v[14:17], v[2:3], off offset:2048
	global_load_dwordx4 v[10:13], v[4:5], off offset:2048
	global_load_dwordx4 v[6:9], v[2:3], off offset:3072
	s_nop 0
	global_load_dwordx4 v[2:5], v[4:5], off offset:3072
	s_lshl_b64 s[6:7], s[6:7], 11
	v_lshl_add_u64 v[54:55], s[18:19], 0, v[42:43]
	s_add_i32 s1, s1, s70
	v_lshl_add_u64 v[42:43], v[42:43], 0, s[16:17]
	v_lshl_add_u64 v[44:45], v[44:45], 0, s[10:11]
	s_cmp_gt_i32 s1, 0x80ff
	s_waitcnt vmcnt(7)
	v_mul_f32_e32 v0, v31, v31
	v_mul_f32_e32 v46, v33, v33
	v_fmac_f32_e32 v0, v30, v30
	v_fmac_f32_e32 v46, v32, v32
	v_add_f32_e32 v0, v0, v46
	s_waitcnt vmcnt(6)
	v_mul_f32_e32 v46, v27, v27
	v_mul_f32_e32 v47, v29, v29
	v_fmac_f32_e32 v46, v26, v26
	v_fmac_f32_e32 v47, v28, v28
	v_add_f32_e32 v46, v46, v47
	s_waitcnt vmcnt(5)
	v_mul_f32_e32 v47, v23, v23
	v_mul_f32_e32 v48, v25, v25
	v_fmac_f32_e32 v47, v22, v22
	v_fmac_f32_e32 v48, v24, v24
	v_add_f32_e32 v47, v47, v48
	v_add_f32_e32 v0, v0, v47
	s_waitcnt vmcnt(4)
	v_mul_f32_e32 v47, v19, v19
	v_mul_f32_e32 v48, v21, v21
	v_fmac_f32_e32 v47, v18, v18
	v_fmac_f32_e32 v48, v20, v20
	v_add_f32_e32 v47, v47, v48
	v_add_f32_e32 v46, v46, v47
	s_waitcnt vmcnt(3)
	v_mul_f32_e32 v47, v15, v15
	v_mul_f32_e32 v48, v17, v17
	v_fmac_f32_e32 v47, v14, v14
	v_fmac_f32_e32 v48, v16, v16
	v_add_f32_e32 v47, v47, v48
	v_add_f32_e32 v0, v0, v47
	s_waitcnt vmcnt(2)
	v_mul_f32_e32 v47, v11, v11
	v_mul_f32_e32 v48, v13, v13
	v_fmac_f32_e32 v47, v10, v10
	v_fmac_f32_e32 v48, v12, v12
	v_add_f32_e32 v47, v47, v48
	v_add_f32_e32 v46, v46, v47
	s_waitcnt vmcnt(1)
	v_mul_f32_e32 v47, v7, v7
	v_mul_f32_e32 v48, v9, v9
	v_fmac_f32_e32 v47, v6, v6
	v_fmac_f32_e32 v48, v8, v8
	v_add_f32_e32 v47, v47, v48
	v_add_f32_e32 v0, v0, v47
	s_waitcnt vmcnt(0)
; __device__ __forceinline__ unsigned pk2(float lo, float hi) { return f2bf(lo) | (f2bf(hi) << 16); }
; __device__ __forceinline__ float wave_sum(float v) { v = dpp_add(v, 0); v = dpp_add(v, 1); v = dpp_add(v, 2); v = dpp_add(v, 3); v = x16_sum(v); return x32_sum(v); }
; __device__ __forceinline__ void rms_row2(const float* xa, const float* xb, const float* g, bf16_t* oa, bf16_t* ob, int lane) {
;     ...
;     const float ra = __builtin_amdgcn_rsqf(wave_sum(sa) * (1.f / 1024.f) + EPS), rb = __builtin_amdgcn_rsqf(wave_sum(sb) * (1.f / 1024.f) + EPS);
;     u32x2* qa = (u32x2*)oa + lane; u32x2* qb = (u32x2*)ob + lane;
; #pragma unroll
;     for (int j = 0; j < 4; ++j) { const f32x4 gg = ((const f32x4*)g)[64 * j + lane]; const f32x4 ta = va[j] * ra * gg, tb = vb[j] * rb * gg;
;         u32x2 p; p.x = pk2(ta.x, ta.y); p.y = pk2(ta.z, ta.w); qa[64 * j] = p; u32x2 q; q.x = pk2(tb.x, tb.y); q.y = pk2(tb.z, tb.w); qb[64 * j] = q; }
; }
	v_mul_f32_e32 v47, v3, v3
	v_mul_f32_e32 v48, v5, v5
	v_add_f32_dpp v0, v0, v0 quad_perm:[1,0,3,2] row_mask:0xf bank_mask:0xf bound_ctrl:1
	v_fmac_f32_e32 v47, v2, v2
	v_fmac_f32_e32 v48, v4, v4
	v_add_f32_dpp v0, v0, v0 quad_perm:[2,3,0,1] row_mask:0xf bank_mask:0xf bound_ctrl:1
	v_add_f32_e32 v47, v47, v48
	v_add_f32_e32 v46, v46, v47
	v_add_f32_dpp v0, v0, v0 row_half_mirror row_mask:0xf bank_mask:0xf bound_ctrl:1
	v_lshl_add_u64 v[48:49], v[38:39], 0, s[6:7]
	v_add_f32_dpp v46, v46, v46 quad_perm:[1,0,3,2] row_mask:0xf bank_mask:0xf bound_ctrl:1
	v_add_f32_dpp v0, v0, v0 row_mirror row_mask:0xf bank_mask:0xf bound_ctrl:1
	v_mov_b32_e32 v47, v0
	s_nop 1
	v_permlane16_swap_b32 v0, v47
	s_nop 1
	v_add_f32_dpp v46, v46, v46 quad_perm:[2,3,0,1] row_mask:0xf bank_mask:0xf bound_ctrl:1
	v_add_f32_e32 v0, v0, v47
	v_mov_b32_e32 v47, v0
	v_add_f32_dpp v46, v46, v46 row_half_mirror row_mask:0xf bank_mask:0xf bound_ctrl:1
	s_nop 1
	v_permlane32_swap_b32 v0, v47
	s_nop 1
	s_mov_b32 s6, 0x4400000
	v_add_f32_e32 v0, v0, v47
	v_add_f32_dpp v46, v46, v46 row_mirror row_mask:0xf bank_mask:0xf bound_ctrl:1
	v_mov_b32_e32 v47, v46
	s_nop 1
	v_permlane16_swap_b32 v46, v47
	s_nop 1
	v_fmamk_f32 v0, v0, 0x3a800000, v198
	v_add_f32_e32 v46, v46, v47
	v_mov_b32_e32 v47, v46
	s_nop 1
	v_permlane32_swap_b32 v46, v47
	s_nop 1
	v_add_f32_e32 v46, v46, v47
	v_rsq_f32_e32 v0, v0
	v_fmamk_f32 v46, v46, 0x3a800000, v198
	v_rsq_f32_e32 v46, v46
	v_pk_mul_f32 v[30:31], v[30:31], v[0:1] op_sel_hi:[1,0]
	v_pk_mul_f32 v[32:33], v[32:33], v[0:1] op_sel_hi:[1,0]
	v_pk_mul_f32 v[26:27], v[26:27], v[46:47] op_sel_hi:[1,0]
	v_pk_mul_f32 v[28:29], v[28:29], v[46:47] op_sel_hi:[1,0]
	v_pk_mul_f32 v[22:23], v[22:23], v[0:1] op_sel_hi:[1,0]
	v_pk_mul_f32 v[18:19], v[18:19], v[46:47] op_sel_hi:[1,0]
	v_pk_mul_f32 v[24:25], v[24:25], v[0:1] op_sel_hi:[1,0]
	v_pk_mul_f32 v[20:21], v[20:21], v[46:47] op_sel_hi:[1,0]
	v_pk_mul_f32 v[14:15], v[14:15], v[0:1] op_sel_hi:[1,0]
	v_pk_mul_f32 v[10:11], v[10:11], v[46:47] op_sel_hi:[1,0]
	v_pk_mul_f32 v[16:17], v[16:17], v[0:1] op_sel_hi:[1,0]
	v_pk_mul_f32 v[12:13], v[12:13], v[46:47] op_sel_hi:[1,0]
	v_pk_mul_f32 v[6:7], v[6:7], v[0:1] op_sel_hi:[1,0]
	v_pk_mul_f32 v[8:9], v[8:9], v[0:1] op_sel_hi:[1,0]
	v_pk_mul_f32 v[2:3], v[2:3], v[46:47] op_sel_hi:[1,0]
	v_pk_mul_f32 v[4:5], v[4:5], v[46:47] op_sel_hi:[1,0]
	v_pk_mul_f32 v[56:57], v[66:67], v[30:31]
	v_pk_mul_f32 v[30:31], v[66:67], v[26:27]
	v_bfe_u32 v26, v56, 16, 1
	v_add3_u32 v26, v56, v26, s31
	v_bfe_u32 v27, v57, 16, 1
	v_pk_mul_f32 v[32:33], v[68:69], v[32:33]
	v_lshrrev_b32_e32 v26, 16, v26
	v_add3_u32 v27, v57, v27, s31
	v_and_or_b32 v50, v27, s77, v26
	v_bfe_u32 v26, v32, 16, 1
	v_add3_u32 v26, v32, v26, s31
	v_bfe_u32 v32, v30, 16, 1
	v_add3_u32 v30, v30, v32, s31
	v_bfe_u32 v32, v31, 16, 1
	v_pk_mul_f32 v[28:29], v[68:69], v[28:29]
	v_lshrrev_b32_e32 v30, 16, v30
	v_add3_u32 v31, v31, v32, s31
	v_bfe_u32 v27, v33, 16, 1
	v_and_or_b32 v30, v31, s77, v30
	v_bfe_u32 v31, v28, 16, 1
	v_lshrrev_b32_e32 v26, 16, v26
	v_add3_u32 v27, v33, v27, s31
	v_add3_u32 v28, v28, v31, s31
	v_bfe_u32 v31, v29, 16, 1
	v_and_or_b32 v51, v27, s77, v26
	v_add_co_u32_e32 v26, vcc, s6, v54
	v_lshrrev_b32_e32 v28, 16, v28
	v_add3_u32 v29, v29, v31, s31
	v_addc_co_u32_e32 v27, vcc, 0, v55, vcc
	v_and_or_b32 v31, v29, s77, v28
	global_store_dwordx2 v[26:27], v[50:51], off
	global_store_dwordx2 v[48:49], v[30:31], off
	v_pk_mul_f32 v[22:23], v[22:23], v[70:71]
	v_pk_mul_f32 v[18:19], v[70:71], v[18:19]
	v_bfe_u32 v28, v22, 16, 1
	v_add3_u32 v22, v22, v28, s31
	v_bfe_u32 v28, v23, 16, 1
	v_pk_mul_f32 v[24:25], v[24:25], v[72:73]
	v_lshrrev_b32_e32 v22, 16, v22
	v_add3_u32 v23, v23, v28, s31
	v_and_or_b32 v22, v23, s77, v22
	v_bfe_u32 v23, v24, 16, 1
	v_add3_u32 v23, v24, v23, s31
	v_bfe_u32 v24, v25, 16, 1
	v_lshrrev_b32_e32 v23, 16, v23
	v_add3_u32 v24, v25, v24, s31
	v_and_or_b32 v23, v24, s77, v23
	global_store_dwordx2 v[26:27], v[22:23], off offset:512
	v_bfe_u32 v22, v18, 16, 1
	v_add3_u32 v18, v18, v22, s31
	v_bfe_u32 v22, v19, 16, 1
	v_pk_mul_f32 v[20:21], v[72:73], v[20:21]
	v_lshrrev_b32_e32 v18, 16, v18
	v_add3_u32 v19, v19, v22, s31
	v_and_or_b32 v18, v19, s77, v18
	v_bfe_u32 v19, v20, 16, 1
	v_add3_u32 v19, v20, v19, s31
	v_bfe_u32 v20, v21, 16, 1
	v_lshrrev_b32_e32 v19, 16, v19
	v_add3_u32 v20, v21, v20, s31
	v_and_or_b32 v19, v20, s77, v19
	global_store_dwordx2 v[48:49], v[18:19], off offset:512
	v_pk_mul_f32 v[14:15], v[14:15], v[74:75]
	v_pk_mul_f32 v[10:11], v[74:75], v[10:11]
	v_bfe_u32 v18, v14, 16, 1
	v_add3_u32 v14, v14, v18, s31
	v_bfe_u32 v18, v15, 16, 1
	v_pk_mul_f32 v[16:17], v[16:17], v[76:77]
	v_lshrrev_b32_e32 v14, 16, v14
	v_add3_u32 v15, v15, v18, s31
	v_and_or_b32 v14, v15, s77, v14
	v_bfe_u32 v15, v16, 16, 1
	v_add3_u32 v15, v16, v15, s31
	v_bfe_u32 v16, v17, 16, 1
	v_lshrrev_b32_e32 v15, 16, v15
	v_add3_u32 v16, v17, v16, s31
	v_and_or_b32 v15, v16, s77, v15
	global_store_dwordx2 v[26:27], v[14:15], off offset:1024
	v_bfe_u32 v14, v10, 16, 1
	v_add3_u32 v10, v10, v14, s31
	v_bfe_u32 v14, v11, 16, 1
	v_pk_mul_f32 v[12:13], v[76:77], v[12:13]
	v_lshrrev_b32_e32 v10, 16, v10
	v_add3_u32 v11, v11, v14, s31
	v_and_or_b32 v10, v11, s77, v10
	v_bfe_u32 v11, v12, 16, 1
	v_add3_u32 v11, v12, v11, s31
	v_bfe_u32 v12, v13, 16, 1
	v_lshrrev_b32_e32 v11, 16, v11
	v_add3_u32 v12, v13, v12, s31
	v_and_or_b32 v11, v12, s77, v11
	global_store_dwordx2 v[48:49], v[10:11], off offset:1024
	v_pk_mul_f32 v[6:7], v[6:7], v[78:79]
	s_nop 0
	v_bfe_u32 v0, v6, 16, 1
	v_add3_u32 v0, v6, v0, s31
	v_bfe_u32 v6, v7, 16, 1
	v_pk_mul_f32 v[8:9], v[8:9], v[80:81]
	v_lshrrev_b32_e32 v0, 16, v0
	v_add3_u32 v6, v7, v6, s31
	v_and_or_b32 v6, v6, s77, v0
	v_bfe_u32 v0, v8, 16, 1
	v_add3_u32 v0, v8, v0, s31
	v_bfe_u32 v7, v9, 16, 1
	v_pk_mul_f32 v[2:3], v[2:3], v[78:79]
	v_lshrrev_b32_e32 v0, 16, v0
	v_add3_u32 v7, v9, v7, s31
	v_and_or_b32 v7, v7, s77, v0
	v_bfe_u32 v0, v2, 16, 1
	v_add3_u32 v0, v2, v0, s31
	v_bfe_u32 v2, v3, 16, 1
	v_pk_mul_f32 v[4:5], v[4:5], v[80:81]
	v_lshrrev_b32_e32 v0, 16, v0
	v_add3_u32 v2, v3, v2, s31
	v_and_or_b32 v2, v2, s77, v0
	v_bfe_u32 v0, v4, 16, 1
	v_add3_u32 v0, v4, v0, s31
	v_bfe_u32 v3, v5, 16, 1
	v_lshrrev_b32_e32 v0, 16, v0
	v_add3_u32 v3, v5, v3, s31
	v_and_or_b32 v3, v3, s77, v0
	global_store_dwordx2 v[26:27], v[6:7], off offset:1536
	global_store_dwordx2 v[48:49], v[2:3], off offset:1536
	s_cbranch_scc0 .LBB0_582
